# MLP-in GEMM: epilogue column info staged into LDS by two in-loop LDS-DMA loads (wave 0, k-tile 12) and read with ds_read; moved row-stat reduction waits with counted vmcnt behind the first store group
# speedup vs baseline: 1.0044x; 1.0035x over previous
;     __device__ __forceinline__ void prep(int pm, int par, LAS unsigned char* lds) const { if (fold) prep_rowstats(stat, pm, par, lds); }
;     __device__ __forceinline__ void prep(int pm, int par, LAS unsigned char* lds) const { if (!ident) prep_rowstats(stat, pm, par, lds); }
;     __device__ __forceinline__ void prep(int pm, int par, LAS unsigned char* lds) const { prep_rowstats(stat, pm, par, lds); }
; template <class Epi>
; __device__ __forceinline__ void gemm_phase(LAS unsigned char* lds, const bf16_t* Ag, const bf16_t* Btg, const int K, const int nM, const int nN, const Epi& E) {
;     ...
;         for (int t = 0; t < nt; t += 2) {
;             const bool last = (t == nt - 2);
;             const char* a1 = cA + (size_t)(t + 1) * kstep;
;             const char* a2 = last ? nA : cA + (size_t)(t + 2) * kstep; const char* b2 = last ? nB : cB + (size_t)(t + 2) * kstep;
;             const char* a3 = a2 + kstep; const char* b3 = b2 + kstep;
;             if (last && has_next && pmn != pm) E.prep(pmn, par ^ 1, lds);
.LBB0_79:
	s_cmp_lg_u32 s73, 12
	s_cselect_b64 s[52:53], -1, 0
	s_cbranch_scc1 .LBB0_78
	v_cmp_gt_u32_e32 vcc, 64, v198
	s_and_saveexec_b64 s[54:55], vcc
	s_cbranch_execz .Lci5_r
	v_lshlrev_b32_e32 v246, 4, v198
	s_lshl_b32 s12, s68, 10
	v_add_u32_e32 v246, s12, v246
	v_mov_b32_e32 v247, 0
	v_lshl_add_u64 v[248:249], s[6:7], 0, v[246:247]
	v_lshl_add_u64 v[246:247], s[22:23], 0, v[246:247]
	s_lshl_b32 s12, s64, 11
	s_add_i32 m0, s12, 0x22000
	s_nop 0
	global_load_lds_dwordx4 v[248:249], off
	s_add_i32 m0, s12, 0x22400
	s_nop 0
	global_load_lds_dwordx4 v[246:247], off
.Lci5_r:
	s_or_b64 exec, exec, s[54:55]
	s_branch .LBB0_78

; #define LAS __attribute__((address_space(3)))
; __device__ __forceinline__ u32x2 pack4(const f32x4 a) { u32x2 v; v.x = cvt_pk_bf16(a[0], a[1]); v.y = cvt_pk_bf16(a[2], a[3]); return v; }
;     __device__ __forceinline__ f32x4 preload(int row, int col) const { return (f32x4){0.f, 0.f, 0.f, 0.f}; }
;     __device__ __forceinline__ u32x2 preload_pk(int row, int col) const { return (u32x2){0u, 0u}; }
;     __device__ __forceinline__ f32x4 preload(int row, int col) const { const u32x2 w = *(const u32x2*)(xb + (size_t)row * DM + col); return (f32x4){bflo(w.x), bfhi(w.x), bflo(w.y), bfhi(w.y)}; }
; __device__ __forceinline__ void prep_rowstats(const float* stat, int pm, int par, LAS unsigned char* lds) {
;     ...
;         for (int q = 0; q < 8; ++q) { const f32x4 v = sp[q]; s1 += v[0] + v[2]; s2 += v[1] + v[3]; }
;         const float mu = s1 * (1.0f / 1024.0f); const float var = fmaxf(s2 * (1.0f / 1024.0f) - mu * mu, 0.f);
;         ((LAS f32x2*)(lds + RS_OFF + par * 2048))[t] = (f32x2){mu, __builtin_amdgcn_rsqf(var + LN_EPS)};
;     __device__ __forceinline__ f32x4 preload(int row, int col) const { return (f32x4){0.f, 0.f, 0.f, 0.f}; }
;     __device__ __forceinline__ u32x2 preload_pk(int row, int col) const { return (u32x2){0u, 0u}; }
;     __device__ __forceinline__ void apply(const RowInfo& ri, const ColInfo& ci, int row, int col, f32x4 a, f32x4 pv, float& s1, float& s2) const {
;         f32x4 v = (a - ci.a * ri.mu) * ri.rstd + ci.b;
; #pragma unroll
;         for (int j = 0; j < 4; ++j) { const float r = fmaxf(v[j], 0.f); v[j] = r * r; }
;         *(u32x2*)(hid + (size_t)row * DFF + col) = pack4(v);
.Lprep5_a:
	v_lshl_or_b32 v188, s68, 8, v185
	v_ashrrev_i32_e32 v189, 31, v188
	s_lshl_b32 s12, s64, 11
	s_add_i32 s12, s12, 0x22000
	v_lshl_add_u32 v190, v185, 2, s12
	ds_read_b128 v[148:151], v190
	ds_read_b128 v[156:159], v190 offset:1024
	ds_read_b128 v[136:139], v190 offset:64
	ds_read_b128 v[140:143], v190 offset:1088
	ds_read_b128 v[128:131], v190 offset:512
	ds_read_b128 v[132:135], v190 offset:1536
	ds_read_b128 v[124:127], v190 offset:576
	ds_read_b128 v[152:155], v190 offset:1600
	s_lshr_b32 s12, s66, 4
	s_lshl_b32 s15, s66, 8
	s_mulk_i32 s12, 0x1040
	s_and_b32 s15, s15, 0xf00
	s_add_i32 s15, s15, s12
	s_add_i32 s12, s14, 0
	s_add_i32 s12, s12, 0x20000
	v_lshl_add_u32 v187, v174, 3, s12
	ds_read_b64 v[172:173], v187
	s_or_b32 s15, s15, 48
	v_add_u32_e32 v190, s15, v174
	v_ashrrev_i32_e32 v191, 31, v190
	v_lshlrev_b64 v[190:191], 13, v[190:191]
	s_waitcnt lgkmcnt(0)
	s_and_b64 vcc, exec, s[40:41]
	v_xor_b32_e32 v151, 0x80000000, v151
	v_xor_b32_e32 v150, 0x80000000, v150
	s_waitcnt lgkmcnt(0)
	v_pk_fma_f32 v[166:167], v[150:151], v[172:173], v[166:167] op_sel_hi:[1,0,1]
	v_pk_fma_f32 v[164:165], v[148:149], v[172:173], v[164:165] op_sel_hi:[1,0,1] neg_lo:[1,0,0] neg_hi:[1,0,0]
	v_pk_fma_f32 v[166:167], v[172:173], v[166:167], v[158:159] op_sel:[1,0,0]
	v_pk_fma_f32 v[164:165], v[172:173], v[164:165], v[156:157] op_sel:[1,0,0]
	v_max_f32_e32 v166, 0, v166
	v_xor_b32_e32 v139, 0x80000000, v139
	v_xor_b32_e32 v138, 0x80000000, v138
	v_pk_fma_f32 v[162:163], v[138:139], v[172:173], v[162:163] op_sel_hi:[1,0,1]
	v_pk_fma_f32 v[160:161], v[136:137], v[172:173], v[160:161] op_sel_hi:[1,0,1] neg_lo:[1,0,0] neg_hi:[1,0,0]
	v_max_f32_e32 v164, 0, v164
	v_max_f32_e32 v165, 0, v165
	v_max_f32_e32 v167, 0, v167
	v_xor_b32_e32 v131, 0x80000000, v131
	v_xor_b32_e32 v130, 0x80000000, v130
	v_pk_fma_f32 v[146:147], v[130:131], v[172:173], v[146:147] op_sel_hi:[1,0,1]
	v_pk_fma_f32 v[144:145], v[128:129], v[172:173], v[144:145] op_sel_hi:[1,0,1] neg_lo:[1,0,0] neg_hi:[1,0,0]
	v_pk_fma_f32 v[162:163], v[172:173], v[162:163], v[142:143] op_sel:[1,0,0]
	v_pk_fma_f32 v[160:161], v[172:173], v[160:161], v[140:141] op_sel:[1,0,0]
	v_xor_b32_e32 v127, 0x80000000, v127
	v_xor_b32_e32 v126, 0x80000000, v126
	v_pk_fma_f32 v[122:123], v[126:127], v[172:173], v[122:123] op_sel_hi:[1,0,1]
	v_pk_fma_f32 v[120:121], v[124:125], v[172:173], v[120:121] op_sel_hi:[1,0,1] neg_lo:[1,0,0] neg_hi:[1,0,0]
	v_pk_fma_f32 v[146:147], v[172:173], v[146:147], v[134:135] op_sel:[1,0,0]
	v_pk_fma_f32 v[144:145], v[172:173], v[144:145], v[132:133] op_sel:[1,0,0]
	v_pk_fma_f32 v[122:123], v[172:173], v[122:123], v[154:155] op_sel:[1,0,0]
	v_pk_fma_f32 v[120:121], v[172:173], v[120:121], v[152:153] op_sel:[1,0,0]
	v_pk_mul_f32 v[164:165], v[164:165], v[164:165]
	v_pk_mul_f32 v[166:167], v[166:167], v[166:167]
	v_max_f32_e32 v160, 0, v160
	v_max_f32_e32 v161, 0, v161
	v_max_f32_e32 v162, 0, v162
	v_max_f32_e32 v163, 0, v163
	v_max_f32_e32 v144, 0, v144
	v_max_f32_e32 v145, 0, v145
	v_max_f32_e32 v146, 0, v146
	v_max_f32_e32 v147, 0, v147
	v_max_f32_e32 v120, 0, v120
	v_max_f32_e32 v121, 0, v121
	v_max_f32_e32 v122, 0, v122
	v_max_f32_e32 v123, 0, v123
	v_cvt_pk_bf16_f32 v192, v164, v165
	v_cvt_pk_bf16_f32 v193, v166, v167
	v_lshl_add_u64 v[166:167], s[86:87], 0, v[190:191]
	v_lshlrev_b64 v[164:165], 1, v[188:189]
	v_pk_mul_f32 v[160:161], v[160:161], v[160:161]
	v_pk_mul_f32 v[162:163], v[162:163], v[162:163]
	v_pk_mul_f32 v[144:145], v[144:145], v[144:145]
	v_pk_mul_f32 v[146:147], v[146:147], v[146:147]
	v_pk_mul_f32 v[120:121], v[120:121], v[120:121]
	v_pk_mul_f32 v[122:123], v[122:123], v[122:123]
	v_lshl_add_u64 v[166:167], v[166:167], 0, v[164:165]
	v_cvt_pk_bf16_f32 v160, v160, v161
	v_cvt_pk_bf16_f32 v161, v162, v163
	v_cvt_pk_bf16_f32 v144, v144, v145
	v_cvt_pk_bf16_f32 v145, v146, v147
	v_cvt_pk_bf16_f32 v120, v120, v121
	v_cvt_pk_bf16_f32 v121, v122, v123
	global_store_dwordx2 v[166:167], v[192:193], off
	global_store_dwordx2 v[166:167], v[160:161], off offset:32
	global_store_dwordx2 v[166:167], v[144:145], off offset:256
	global_store_dwordx2 v[166:167], v[120:121], off offset:288
	s_cmp_lg_u32 s48, 0
	s_cbranch_scc1 .Lprep5_b
	s_waitcnt vmcnt(4)
	v_pk_add_f32 v[248:249], v[232:233], v[234:235]
	v_pk_add_f32 v[250:251], v[236:237], v[238:239]
	v_pk_add_f32 v[248:249], v[248:249], v[250:251]
	v_pk_add_f32 v[250:251], v[240:241], v[242:243]
	v_pk_add_f32 v[248:249], v[248:249], v[250:251]
	v_pk_add_f32 v[250:251], v[244:245], v[246:247]
	v_pk_add_f32 v[248:249], v[248:249], v[250:251]
	s_nop 1
	v_mov_b32_dpp v250, v248 quad_perm:[1,0,3,2] row_mask:0xf bank_mask:0xf
	v_mov_b32_dpp v251, v249 quad_perm:[1,0,3,2] row_mask:0xf bank_mask:0xf
	s_nop 0
	v_pk_add_f32 v[248:249], v[248:249], v[250:251]
	v_pk_mul_f32 v[248:249], v[248:249], s[0:1] op_sel_hi:[1,0]
	s_nop 0
	v_fma_f32 v249, -v248, v248, v249
	v_max_f32_e32 v249, 0, v249
	v_add_f32_e32 v249, 0x3727c5ac, v249
	v_rsq_f32_e32 v249, v249
	s_nop 0
	ds_write_b64 v226, v[248:249]
; __device__ __forceinline__ float bflo(unsigned w) { return __uint_as_float(w << 16); }
; __device__ __forceinline__ float bfhi(unsigned w) { return __uint_as_float(w & 0xffff0000u); }
;     __device__ __forceinline__ void apply(const RowInfo& ri, const ColInfo& ci, int row, int col, f32x4 a, f32x4 pv, float& s1, float& s2) const {
;         f32x4 v = (a - ci.a * ri.mu) * ri.rstd + ci.b;
; #pragma unroll
;         for (int j = 0; j < 4; ++j) { const float r = fmaxf(v[j], 0.f); v[j] = r * r; }
;         *(u32x2*)(hid + (size_t)row * DFF + col) = pack4(v);
; template <class Epi>
; __device__ __forceinline__ void gemm_phase(LAS unsigned char* lds, const bf16_t* Ag, const bf16_t* Btg, const int K, const int nM, const int nN, const Epi& E) {
;     ...
;             for (int gi = 0; gi < 8; ++gi) {
;                 const int ai = gi >> 2, m = gi & 3;
;                 const int lrow = ai * 128 + wr * 64 + m * 16 + fr, row = prow0(pm) + lrow;
;                 if (!Epi::PRELOAD && gi == 0) {
; #pragma unroll
;                     for (int g2 = 0; g2 < 4; ++g2)
; #pragma unroll
;                         for (int bj = 0; bj < 2; ++bj)
; #pragma unroll
;                             for (int n = 0; n < 2; ++n) pk[g2][bj][n] = (u32x2){0u, 0u};
;                 }
;                 if (Epi::PRELOAD && m == 0) {
; #pragma unroll
;                     for (int g2 = 0; g2 < 4; ++g2)
; #pragma unroll
;                         for (int bj = 0; bj < 2; ++bj)
; #pragma unroll
;                             for (int n = 0; n < 2; ++n) pk[g2][bj][n] = E.preload_pk(prow0(pm) + ai * 128 + wr * 64 + g2 * 16 + fr, pn * 256 + bj * 128 + wc * 32 + n * 16 + fq * 4);
;                 }
;                 f32x4 pv[2][2];
; #pragma unroll
;                 for (int bj = 0; bj < 2; ++bj)
; #pragma unroll
;                     for (int n = 0; n < 2; ++n) { const u32x2 w = pk[m][bj][n]; pv[bj][n] = (f32x4){bflo(w.x), bfhi(w.x), bflo(w.y), bfhi(w.y)}; }
;                 const RowInfo ri = E.rowinfo(row, lrow, par, lds);
;                 float s1 = 0.f, s2 = 0.f;
; #pragma unroll
;                 for (int bj = 0; bj < 2; ++bj)
; #pragma unroll
;                     for (int n = 0; n < 2; ++n) E.apply(ri, ci[bj][n], row, pn * 256 + bj * 128 + wc * 32 + n * 16 + fq * 4, acc[ai][bj][m][n], pv[bj][n], s1, s2);
.Lprep5_b:
	ds_read_b64 v[122:123], v187 offset:128
	v_add_u32_e32 v120, s15, v176
	v_ashrrev_i32_e32 v121, 31, v120
	v_lshlrev_b64 v[120:121], 13, v[120:121]
	s_waitcnt lgkmcnt(0)
	v_pk_fma_f32 v[118:119], v[150:151], v[122:123], v[118:119] op_sel_hi:[1,0,1]
	v_pk_fma_f32 v[116:117], v[148:149], v[122:123], v[116:117] op_sel_hi:[1,0,1] neg_lo:[1,0,0] neg_hi:[1,0,0]
	v_pk_fma_f32 v[118:119], v[122:123], v[118:119], v[158:159] op_sel:[1,0,0]
	v_pk_fma_f32 v[116:117], v[122:123], v[116:117], v[156:157] op_sel:[1,0,0]
	v_pk_fma_f32 v[114:115], v[138:139], v[122:123], v[114:115] op_sel_hi:[1,0,1]
	v_pk_fma_f32 v[112:113], v[136:137], v[122:123], v[112:113] op_sel_hi:[1,0,1] neg_lo:[1,0,0] neg_hi:[1,0,0]
	v_pk_fma_f32 v[110:111], v[130:131], v[122:123], v[110:111] op_sel_hi:[1,0,1]
	v_pk_fma_f32 v[108:109], v[128:129], v[122:123], v[108:109] op_sel_hi:[1,0,1] neg_lo:[1,0,0] neg_hi:[1,0,0]
	v_pk_fma_f32 v[106:107], v[126:127], v[122:123], v[106:107] op_sel_hi:[1,0,1]
	v_pk_fma_f32 v[104:105], v[124:125], v[122:123], v[104:105] op_sel_hi:[1,0,1] neg_lo:[1,0,0] neg_hi:[1,0,0]
	v_max_f32_e32 v116, 0, v116
	v_max_f32_e32 v117, 0, v117
	v_max_f32_e32 v118, 0, v118
	v_max_f32_e32 v119, 0, v119
	v_pk_fma_f32 v[114:115], v[122:123], v[114:115], v[142:143] op_sel:[1,0,0]
	v_pk_fma_f32 v[112:113], v[122:123], v[112:113], v[140:141] op_sel:[1,0,0]
	v_pk_fma_f32 v[110:111], v[122:123], v[110:111], v[134:135] op_sel:[1,0,0]
	v_pk_fma_f32 v[108:109], v[122:123], v[108:109], v[132:133] op_sel:[1,0,0]
	v_pk_fma_f32 v[106:107], v[122:123], v[106:107], v[154:155] op_sel:[1,0,0]
	v_pk_fma_f32 v[104:105], v[122:123], v[104:105], v[152:153] op_sel:[1,0,0]
	v_pk_mul_f32 v[116:117], v[116:117], v[116:117]
	v_pk_mul_f32 v[118:119], v[118:119], v[118:119]
	v_max_f32_e32 v112, 0, v112
	v_max_f32_e32 v113, 0, v113
	v_max_f32_e32 v114, 0, v114
	v_max_f32_e32 v115, 0, v115
	v_max_f32_e32 v108, 0, v108
	v_max_f32_e32 v109, 0, v109
	v_max_f32_e32 v110, 0, v110
	v_max_f32_e32 v111, 0, v111
	v_max_f32_e32 v104, 0, v104
	v_max_f32_e32 v105, 0, v105
	v_max_f32_e32 v106, 0, v106
	v_max_f32_e32 v107, 0, v107
	v_cvt_pk_bf16_f32 v116, v116, v117
	v_cvt_pk_bf16_f32 v117, v118, v119
	v_lshl_add_u64 v[118:119], s[86:87], 0, v[120:121]
	v_pk_mul_f32 v[112:113], v[112:113], v[112:113]
	v_pk_mul_f32 v[114:115], v[114:115], v[114:115]
	v_pk_mul_f32 v[108:109], v[108:109], v[108:109]
	v_pk_mul_f32 v[110:111], v[110:111], v[110:111]
	v_pk_mul_f32 v[104:105], v[104:105], v[104:105]
	v_pk_mul_f32 v[106:107], v[106:107], v[106:107]
	v_lshl_add_u64 v[118:119], v[118:119], 0, v[164:165]
	v_cvt_pk_bf16_f32 v112, v112, v113
	v_cvt_pk_bf16_f32 v113, v114, v115
	v_cvt_pk_bf16_f32 v108, v108, v109
	v_cvt_pk_bf16_f32 v109, v110, v111
	v_cvt_pk_bf16_f32 v104, v104, v105
	v_cvt_pk_bf16_f32 v105, v106, v107
	global_store_dwordx2 v[118:119], v[116:117], off
	global_store_dwordx2 v[118:119], v[112:113], off offset:32
	global_store_dwordx2 v[118:119], v[108:109], off offset:256
	global_store_dwordx2 v[118:119], v[104:105], off offset:288
	ds_read_b64 v[106:107], v187 offset:256
	v_add_u32_e32 v104, s15, v179
	v_ashrrev_i32_e32 v105, 31, v104
	v_lshlrev_b64 v[104:105], 13, v[104:105]
	s_waitcnt lgkmcnt(0)
	v_pk_fma_f32 v[102:103], v[150:151], v[106:107], v[102:103] op_sel_hi:[1,0,1]
	v_pk_fma_f32 v[100:101], v[148:149], v[106:107], v[100:101] op_sel_hi:[1,0,1] neg_lo:[1,0,0] neg_hi:[1,0,0]
	v_pk_fma_f32 v[102:103], v[106:107], v[102:103], v[158:159] op_sel:[1,0,0]
	v_pk_fma_f32 v[100:101], v[106:107], v[100:101], v[156:157] op_sel:[1,0,0]
	v_pk_fma_f32 v[98:99], v[138:139], v[106:107], v[98:99] op_sel_hi:[1,0,1]
	v_pk_fma_f32 v[96:97], v[136:137], v[106:107], v[96:97] op_sel_hi:[1,0,1] neg_lo:[1,0,0] neg_hi:[1,0,0]
	v_pk_fma_f32 v[94:95], v[130:131], v[106:107], v[94:95] op_sel_hi:[1,0,1]
	v_pk_fma_f32 v[92:93], v[128:129], v[106:107], v[92:93] op_sel_hi:[1,0,1] neg_lo:[1,0,0] neg_hi:[1,0,0]
	v_pk_fma_f32 v[90:91], v[126:127], v[106:107], v[90:91] op_sel_hi:[1,0,1]
	v_pk_fma_f32 v[88:89], v[124:125], v[106:107], v[88:89] op_sel_hi:[1,0,1] neg_lo:[1,0,0] neg_hi:[1,0,0]
	v_max_f32_e32 v100, 0, v100
	v_max_f32_e32 v101, 0, v101
	v_max_f32_e32 v102, 0, v102
	v_max_f32_e32 v103, 0, v103
	v_pk_fma_f32 v[98:99], v[106:107], v[98:99], v[142:143] op_sel:[1,0,0]
	v_pk_fma_f32 v[96:97], v[106:107], v[96:97], v[140:141] op_sel:[1,0,0]
	v_pk_fma_f32 v[94:95], v[106:107], v[94:95], v[134:135] op_sel:[1,0,0]
	v_pk_fma_f32 v[92:93], v[106:107], v[92:93], v[132:133] op_sel:[1,0,0]
	v_pk_fma_f32 v[90:91], v[106:107], v[90:91], v[154:155] op_sel:[1,0,0]
	v_pk_fma_f32 v[88:89], v[106:107], v[88:89], v[152:153] op_sel:[1,0,0]
	v_pk_mul_f32 v[100:101], v[100:101], v[100:101]
	v_pk_mul_f32 v[102:103], v[102:103], v[102:103]
	v_max_f32_e32 v96, 0, v96
	v_max_f32_e32 v97, 0, v97
	v_max_f32_e32 v98, 0, v98
	v_max_f32_e32 v99, 0, v99
	v_max_f32_e32 v92, 0, v92
	v_max_f32_e32 v93, 0, v93
	v_max_f32_e32 v94, 0, v94
	v_max_f32_e32 v95, 0, v95
	v_max_f32_e32 v88, 0, v88
	v_max_f32_e32 v89, 0, v89
	v_max_f32_e32 v90, 0, v90
	v_max_f32_e32 v91, 0, v91
	v_cvt_pk_bf16_f32 v100, v100, v101
	v_cvt_pk_bf16_f32 v101, v102, v103
	v_lshl_add_u64 v[102:103], s[86:87], 0, v[104:105]
	v_pk_mul_f32 v[96:97], v[96:97], v[96:97]
	v_pk_mul_f32 v[98:99], v[98:99], v[98:99]
	v_pk_mul_f32 v[92:93], v[92:93], v[92:93]
	v_pk_mul_f32 v[94:95], v[94:95], v[94:95]
	v_pk_mul_f32 v[88:89], v[88:89], v[88:89]
	v_pk_mul_f32 v[90:91], v[90:91], v[90:91]
	v_lshl_add_u64 v[102:103], v[102:103], 0, v[164:165]
	v_cvt_pk_bf16_f32 v96, v96, v97
	v_cvt_pk_bf16_f32 v97, v98, v99
	v_cvt_pk_bf16_f32 v92, v92, v93
	v_cvt_pk_bf16_f32 v93, v94, v95
	v_cvt_pk_bf16_f32 v88, v88, v89
	v_cvt_pk_bf16_f32 v89, v90, v91
	global_store_dwordx2 v[102:103], v[100:101], off
	global_store_dwordx2 v[102:103], v[96:97], off offset:32
	global_store_dwordx2 v[102:103], v[92:93], off offset:256
	global_store_dwordx2 v[102:103], v[88:89], off offset:288
	ds_read_b64 v[90:91], v187 offset:384
	v_add_u32_e32 v88, s15, v180
	v_ashrrev_i32_e32 v89, 31, v88
	v_lshlrev_b64 v[88:89], 13, v[88:89]
	s_waitcnt lgkmcnt(0)
; __device__ __forceinline__ float bflo(unsigned w) { return __uint_as_float(w << 16); }
; __device__ __forceinline__ float bfhi(unsigned w) { return __uint_as_float(w & 0xffff0000u); }
;     __device__ __forceinline__ void apply(const RowInfo& ri, const ColInfo& ci, int row, int col, f32x4 a, f32x4 pv, float& s1, float& s2) const {
;         f32x4 v = (a - ci.a * ri.mu) * ri.rstd + ci.b;
; #pragma unroll
;         for (int j = 0; j < 4; ++j) { const float r = fmaxf(v[j], 0.f); v[j] = r * r; }
;         *(u32x2*)(hid + (size_t)row * DFF + col) = pack4(v);
; template <class Epi>
; __device__ __forceinline__ void gemm_phase(LAS unsigned char* lds, const bf16_t* Ag, const bf16_t* Btg, const int K, const int nM, const int nN, const Epi& E) {
;     ...
;             for (int gi = 0; gi < 8; ++gi) {
;                 const int ai = gi >> 2, m = gi & 3;
;                 const int lrow = ai * 128 + wr * 64 + m * 16 + fr, row = prow0(pm) + lrow;
;                 if (!Epi::PRELOAD && gi == 0) {
; #pragma unroll
;                     for (int g2 = 0; g2 < 4; ++g2)
; #pragma unroll
;                         for (int bj = 0; bj < 2; ++bj)
; #pragma unroll
;                             for (int n = 0; n < 2; ++n) pk[g2][bj][n] = (u32x2){0u, 0u};
;                 }
;                 if (Epi::PRELOAD && m == 0) {
; #pragma unroll
;                     for (int g2 = 0; g2 < 4; ++g2)
; #pragma unroll
;                         for (int bj = 0; bj < 2; ++bj)
; #pragma unroll
;                             for (int n = 0; n < 2; ++n) pk[g2][bj][n] = E.preload_pk(prow0(pm) + ai * 128 + wr * 64 + g2 * 16 + fr, pn * 256 + bj * 128 + wc * 32 + n * 16 + fq * 4);
;                 }
;                 f32x4 pv[2][2];
; #pragma unroll
;                 for (int bj = 0; bj < 2; ++bj)
; #pragma unroll
;                     for (int n = 0; n < 2; ++n) { const u32x2 w = pk[m][bj][n]; pv[bj][n] = (f32x4){bflo(w.x), bfhi(w.x), bflo(w.y), bfhi(w.y)}; }
;                 const RowInfo ri = E.rowinfo(row, lrow, par, lds);
;                 float s1 = 0.f, s2 = 0.f;
; #pragma unroll
;                 for (int bj = 0; bj < 2; ++bj)
; #pragma unroll
;                     for (int n = 0; n < 2; ++n) E.apply(ri, ci[bj][n], row, pn * 256 + bj * 128 + wc * 32 + n * 16 + fq * 4, acc[ai][bj][m][n], pv[bj][n], s1, s2);
	v_pk_fma_f32 v[86:87], v[150:151], v[90:91], v[86:87] op_sel_hi:[1,0,1]
	v_pk_fma_f32 v[84:85], v[148:149], v[90:91], v[84:85] op_sel_hi:[1,0,1] neg_lo:[1,0,0] neg_hi:[1,0,0]
	v_pk_fma_f32 v[86:87], v[90:91], v[86:87], v[158:159] op_sel:[1,0,0]
	v_pk_fma_f32 v[84:85], v[90:91], v[84:85], v[156:157] op_sel:[1,0,0]
	v_pk_fma_f32 v[82:83], v[138:139], v[90:91], v[82:83] op_sel_hi:[1,0,1]
	v_pk_fma_f32 v[80:81], v[136:137], v[90:91], v[80:81] op_sel_hi:[1,0,1] neg_lo:[1,0,0] neg_hi:[1,0,0]
	v_pk_fma_f32 v[78:79], v[130:131], v[90:91], v[78:79] op_sel_hi:[1,0,1]
	v_pk_fma_f32 v[76:77], v[128:129], v[90:91], v[76:77] op_sel_hi:[1,0,1] neg_lo:[1,0,0] neg_hi:[1,0,0]
	v_pk_fma_f32 v[74:75], v[126:127], v[90:91], v[74:75] op_sel_hi:[1,0,1]
	v_pk_fma_f32 v[72:73], v[124:125], v[90:91], v[72:73] op_sel_hi:[1,0,1] neg_lo:[1,0,0] neg_hi:[1,0,0]
	v_max_f32_e32 v84, 0, v84
	v_max_f32_e32 v85, 0, v85
	v_max_f32_e32 v86, 0, v86
	v_max_f32_e32 v87, 0, v87
	v_pk_fma_f32 v[82:83], v[90:91], v[82:83], v[142:143] op_sel:[1,0,0]
	v_pk_fma_f32 v[80:81], v[90:91], v[80:81], v[140:141] op_sel:[1,0,0]
	v_pk_fma_f32 v[78:79], v[90:91], v[78:79], v[134:135] op_sel:[1,0,0]
	v_pk_fma_f32 v[76:77], v[90:91], v[76:77], v[132:133] op_sel:[1,0,0]
	v_pk_fma_f32 v[74:75], v[90:91], v[74:75], v[154:155] op_sel:[1,0,0]
	v_pk_fma_f32 v[72:73], v[90:91], v[72:73], v[152:153] op_sel:[1,0,0]
	v_pk_mul_f32 v[84:85], v[84:85], v[84:85]
	v_pk_mul_f32 v[86:87], v[86:87], v[86:87]
	v_max_f32_e32 v80, 0, v80
	v_max_f32_e32 v81, 0, v81
	v_max_f32_e32 v82, 0, v82
	v_max_f32_e32 v83, 0, v83
	v_max_f32_e32 v76, 0, v76
	v_max_f32_e32 v77, 0, v77
	v_max_f32_e32 v78, 0, v78
	v_max_f32_e32 v79, 0, v79
	v_max_f32_e32 v72, 0, v72
	v_max_f32_e32 v73, 0, v73
	v_max_f32_e32 v74, 0, v74
	v_max_f32_e32 v75, 0, v75
	v_cvt_pk_bf16_f32 v84, v84, v85
	v_cvt_pk_bf16_f32 v85, v86, v87
	v_lshl_add_u64 v[86:87], s[86:87], 0, v[88:89]
	v_pk_mul_f32 v[80:81], v[80:81], v[80:81]
	v_pk_mul_f32 v[82:83], v[82:83], v[82:83]
	v_pk_mul_f32 v[76:77], v[76:77], v[76:77]
	v_pk_mul_f32 v[78:79], v[78:79], v[78:79]
	v_pk_mul_f32 v[72:73], v[72:73], v[72:73]
	v_pk_mul_f32 v[74:75], v[74:75], v[74:75]
	v_lshl_add_u64 v[86:87], v[86:87], 0, v[164:165]
	v_cvt_pk_bf16_f32 v80, v80, v81
	v_cvt_pk_bf16_f32 v81, v82, v83
	v_cvt_pk_bf16_f32 v76, v76, v77
	v_cvt_pk_bf16_f32 v77, v78, v79
	v_cvt_pk_bf16_f32 v72, v72, v73
	v_cvt_pk_bf16_f32 v73, v74, v75
	global_store_dwordx2 v[86:87], v[84:85], off
	global_store_dwordx2 v[86:87], v[80:81], off offset:32
	global_store_dwordx2 v[86:87], v[76:77], off offset:256
	global_store_dwordx2 v[86:87], v[72:73], off offset:288
	ds_read_b64 v[74:75], v187 offset:1024
	v_add_u32_e32 v72, s15, v181
	v_ashrrev_i32_e32 v73, 31, v72
	v_lshlrev_b64 v[72:73], 13, v[72:73]
	s_waitcnt lgkmcnt(0)
	v_pk_fma_f32 v[62:63], v[150:151], v[74:75], v[62:63] op_sel_hi:[1,0,1]
	v_pk_fma_f32 v[60:61], v[148:149], v[74:75], v[60:61] op_sel_hi:[1,0,1] neg_lo:[1,0,0] neg_hi:[1,0,0]
	v_pk_fma_f32 v[62:63], v[74:75], v[62:63], v[158:159] op_sel:[1,0,0]
	v_pk_fma_f32 v[60:61], v[74:75], v[60:61], v[156:157] op_sel:[1,0,0]
	v_pk_fma_f32 v[58:59], v[138:139], v[74:75], v[58:59] op_sel_hi:[1,0,1]
	v_pk_fma_f32 v[56:57], v[136:137], v[74:75], v[56:57] op_sel_hi:[1,0,1] neg_lo:[1,0,0] neg_hi:[1,0,0]
	v_max_f32_e32 v60, 0, v60
	v_max_f32_e32 v61, 0, v61
	v_max_f32_e32 v62, 0, v62
	v_max_f32_e32 v63, 0, v63
	v_pk_fma_f32 v[58:59], v[74:75], v[58:59], v[142:143] op_sel:[1,0,0]
	v_pk_fma_f32 v[56:57], v[74:75], v[56:57], v[140:141] op_sel:[1,0,0]
	v_pk_mul_f32 v[60:61], v[60:61], v[60:61]
	v_pk_mul_f32 v[62:63], v[62:63], v[62:63]
	v_max_f32_e32 v56, 0, v56
	v_max_f32_e32 v57, 0, v57
	v_max_f32_e32 v58, 0, v58
	v_max_f32_e32 v59, 0, v59
	v_cvt_pk_bf16_f32 v60, v60, v61
	v_cvt_pk_bf16_f32 v61, v62, v63
	v_lshl_add_u64 v[62:63], s[86:87], 0, v[72:73]
	v_pk_mul_f32 v[56:57], v[56:57], v[56:57]
	v_pk_mul_f32 v[58:59], v[58:59], v[58:59]
	v_lshl_add_u64 v[62:63], v[62:63], 0, v[164:165]
	v_cvt_pk_bf16_f32 v56, v56, v57
	v_cvt_pk_bf16_f32 v57, v58, v59
	global_store_dwordx2 v[62:63], v[56:57], off offset:32
	v_pk_fma_f32 v[56:57], v[130:131], v[74:75], v[70:71] op_sel_hi:[1,0,1]
	v_pk_fma_f32 v[58:59], v[128:129], v[74:75], v[68:69] op_sel_hi:[1,0,1] neg_lo:[1,0,0] neg_hi:[1,0,0]
	v_pk_fma_f32 v[56:57], v[74:75], v[56:57], v[134:135] op_sel:[1,0,0]
	v_pk_fma_f32 v[58:59], v[74:75], v[58:59], v[132:133] op_sel:[1,0,0]
	v_max_f32_e32 v56, 0, v56
	v_max_f32_e32 v58, 0, v58
	v_max_f32_e32 v59, 0, v59
	v_max_f32_e32 v57, 0, v57
	v_pk_mul_f32 v[58:59], v[58:59], v[58:59]
	v_pk_mul_f32 v[56:57], v[56:57], v[56:57]
	v_cvt_pk_bf16_f32 v58, v58, v59
	v_cvt_pk_bf16_f32 v59, v56, v57
	global_store_dwordx2 v[62:63], v[58:59], off offset:256
	v_pk_fma_f32 v[56:57], v[126:127], v[74:75], v[66:67] op_sel_hi:[1,0,1]
	v_pk_fma_f32 v[58:59], v[124:125], v[74:75], v[64:65] op_sel_hi:[1,0,1] neg_lo:[1,0,0] neg_hi:[1,0,0]
	v_pk_fma_f32 v[56:57], v[74:75], v[56:57], v[154:155] op_sel:[1,0,0]
	v_pk_fma_f32 v[58:59], v[74:75], v[58:59], v[152:153] op_sel:[1,0,0]
	v_max_f32_e32 v56, 0, v56
	v_max_f32_e32 v58, 0, v58
	v_max_f32_e32 v59, 0, v59
	v_max_f32_e32 v57, 0, v57
	v_pk_mul_f32 v[58:59], v[58:59], v[58:59]
	v_pk_mul_f32 v[56:57], v[56:57], v[56:57]
	v_cvt_pk_bf16_f32 v58, v58, v59
	v_cvt_pk_bf16_f32 v59, v56, v57
	global_store_dwordx2 v[62:63], v[60:61], off
	global_store_dwordx2 v[62:63], v[58:59], off offset:288
	ds_read_b64 v[58:59], v187 offset:1152
	v_add_u32_e32 v56, s15, v182
	v_ashrrev_i32_e32 v57, 31, v56
	v_lshlrev_b64 v[56:57], 13, v[56:57]
	s_waitcnt lgkmcnt(0)
; __device__ __forceinline__ float bflo(unsigned w) { return __uint_as_float(w << 16); }
; __device__ __forceinline__ float bfhi(unsigned w) { return __uint_as_float(w & 0xffff0000u); }
;     __device__ __forceinline__ void apply(const RowInfo& ri, const ColInfo& ci, int row, int col, f32x4 a, f32x4 pv, float& s1, float& s2) const {
;         f32x4 v = (a - ci.a * ri.mu) * ri.rstd + ci.b;
; #pragma unroll
;         for (int j = 0; j < 4; ++j) { const float r = fmaxf(v[j], 0.f); v[j] = r * r; }
;         *(u32x2*)(hid + (size_t)row * DFF + col) = pack4(v);
; template <class Epi>
; __device__ __forceinline__ void gemm_phase(LAS unsigned char* lds, const bf16_t* Ag, const bf16_t* Btg, const int K, const int nM, const int nN, const Epi& E) {
;     ...
;             for (int gi = 0; gi < 8; ++gi) {
;                 const int ai = gi >> 2, m = gi & 3;
;                 const int lrow = ai * 128 + wr * 64 + m * 16 + fr, row = prow0(pm) + lrow;
;                 if (!Epi::PRELOAD && gi == 0) {
; #pragma unroll
;                     for (int g2 = 0; g2 < 4; ++g2)
; #pragma unroll
;                         for (int bj = 0; bj < 2; ++bj)
; #pragma unroll
;                             for (int n = 0; n < 2; ++n) pk[g2][bj][n] = (u32x2){0u, 0u};
;                 }
;                 if (Epi::PRELOAD && m == 0) {
; #pragma unroll
;                     for (int g2 = 0; g2 < 4; ++g2)
; #pragma unroll
;                         for (int bj = 0; bj < 2; ++bj)
; #pragma unroll
;                             for (int n = 0; n < 2; ++n) pk[g2][bj][n] = E.preload_pk(prow0(pm) + ai * 128 + wr * 64 + g2 * 16 + fr, pn * 256 + bj * 128 + wc * 32 + n * 16 + fq * 4);
;                 }
;                 f32x4 pv[2][2];
; #pragma unroll
;                 for (int bj = 0; bj < 2; ++bj)
; #pragma unroll
;                     for (int n = 0; n < 2; ++n) { const u32x2 w = pk[m][bj][n]; pv[bj][n] = (f32x4){bflo(w.x), bfhi(w.x), bflo(w.y), bfhi(w.y)}; }
;                 const RowInfo ri = E.rowinfo(row, lrow, par, lds);
;                 float s1 = 0.f, s2 = 0.f;
; #pragma unroll
;                 for (int bj = 0; bj < 2; ++bj)
; #pragma unroll
;                     for (int n = 0; n < 2; ++n) E.apply(ri, ci[bj][n], row, pn * 256 + bj * 128 + wc * 32 + n * 16 + fq * 4, acc[ai][bj][m][n], pv[bj][n], s1, s2);
	v_pk_fma_f32 v[46:47], v[150:151], v[58:59], v[46:47] op_sel_hi:[1,0,1]
	v_pk_fma_f32 v[44:45], v[148:149], v[58:59], v[44:45] op_sel_hi:[1,0,1] neg_lo:[1,0,0] neg_hi:[1,0,0]
	v_pk_fma_f32 v[46:47], v[58:59], v[46:47], v[158:159] op_sel:[1,0,0]
	v_pk_fma_f32 v[44:45], v[58:59], v[44:45], v[156:157] op_sel:[1,0,0]
	v_pk_fma_f32 v[42:43], v[138:139], v[58:59], v[42:43] op_sel_hi:[1,0,1]
	v_pk_fma_f32 v[40:41], v[136:137], v[58:59], v[40:41] op_sel_hi:[1,0,1] neg_lo:[1,0,0] neg_hi:[1,0,0]
	v_max_f32_e32 v44, 0, v44
	v_max_f32_e32 v45, 0, v45
	v_max_f32_e32 v46, 0, v46
	v_max_f32_e32 v47, 0, v47
	v_pk_fma_f32 v[42:43], v[58:59], v[42:43], v[142:143] op_sel:[1,0,0]
	v_pk_fma_f32 v[40:41], v[58:59], v[40:41], v[140:141] op_sel:[1,0,0]
	v_pk_mul_f32 v[44:45], v[44:45], v[44:45]
	v_pk_mul_f32 v[46:47], v[46:47], v[46:47]
	v_max_f32_e32 v40, 0, v40
	v_max_f32_e32 v41, 0, v41
	v_max_f32_e32 v42, 0, v42
	v_max_f32_e32 v43, 0, v43
	v_cvt_pk_bf16_f32 v44, v44, v45
	v_cvt_pk_bf16_f32 v45, v46, v47
	v_lshl_add_u64 v[46:47], s[86:87], 0, v[56:57]
	v_pk_mul_f32 v[40:41], v[40:41], v[40:41]
	v_pk_mul_f32 v[42:43], v[42:43], v[42:43]
	v_lshl_add_u64 v[46:47], v[46:47], 0, v[164:165]
	v_cvt_pk_bf16_f32 v40, v40, v41
	v_cvt_pk_bf16_f32 v41, v42, v43
	global_store_dwordx2 v[46:47], v[40:41], off offset:32
	v_pk_fma_f32 v[40:41], v[130:131], v[58:59], v[54:55] op_sel_hi:[1,0,1]
	v_pk_fma_f32 v[42:43], v[128:129], v[58:59], v[52:53] op_sel_hi:[1,0,1] neg_lo:[1,0,0] neg_hi:[1,0,0]
	v_pk_fma_f32 v[40:41], v[58:59], v[40:41], v[134:135] op_sel:[1,0,0]
	v_pk_fma_f32 v[42:43], v[58:59], v[42:43], v[132:133] op_sel:[1,0,0]
	v_max_f32_e32 v40, 0, v40
	v_max_f32_e32 v42, 0, v42
	v_max_f32_e32 v43, 0, v43
	v_max_f32_e32 v41, 0, v41
	v_pk_mul_f32 v[42:43], v[42:43], v[42:43]
	v_pk_mul_f32 v[40:41], v[40:41], v[40:41]
	v_cvt_pk_bf16_f32 v42, v42, v43
	v_cvt_pk_bf16_f32 v43, v40, v41
	global_store_dwordx2 v[46:47], v[42:43], off offset:256
	v_pk_fma_f32 v[40:41], v[126:127], v[58:59], v[50:51] op_sel_hi:[1,0,1]
	v_pk_fma_f32 v[42:43], v[124:125], v[58:59], v[48:49] op_sel_hi:[1,0,1] neg_lo:[1,0,0] neg_hi:[1,0,0]
	v_pk_fma_f32 v[40:41], v[58:59], v[40:41], v[154:155] op_sel:[1,0,0]
	v_pk_fma_f32 v[42:43], v[58:59], v[42:43], v[152:153] op_sel:[1,0,0]
	v_max_f32_e32 v40, 0, v40
	v_max_f32_e32 v42, 0, v42
	v_max_f32_e32 v43, 0, v43
	v_max_f32_e32 v41, 0, v41
	v_pk_mul_f32 v[42:43], v[42:43], v[42:43]
	v_pk_mul_f32 v[40:41], v[40:41], v[40:41]
	v_cvt_pk_bf16_f32 v42, v42, v43
	v_cvt_pk_bf16_f32 v43, v40, v41
	global_store_dwordx2 v[46:47], v[44:45], off
	global_store_dwordx2 v[46:47], v[42:43], off offset:288
	ds_read_b64 v[42:43], v187 offset:1280
	v_add_u32_e32 v40, s15, v183
	v_ashrrev_i32_e32 v41, 31, v40
	v_lshlrev_b64 v[40:41], 13, v[40:41]
	s_waitcnt lgkmcnt(0)
; __device__ __forceinline__ u32x2 pack4(const f32x4 a) { u32x2 v; v.x = cvt_pk_bf16(a[0], a[1]); v.y = cvt_pk_bf16(a[2], a[3]); return v; }
;     __device__ __forceinline__ void apply(const RowInfo& ri, const ColInfo& ci, int row, int col, f32x4 a, f32x4 pv, float& s1, float& s2) const {
;         f32x4 v = (a - ci.a * ri.mu) * ri.rstd + ci.b;
; #pragma unroll
;         for (int j = 0; j < 4; ++j) { const float r = fmaxf(v[j], 0.f); v[j] = r * r; }
;         *(u32x2*)(hid + (size_t)row * DFF + col) = pack4(v);
; template <class Epi>
; __device__ __forceinline__ void gemm_phase(LAS unsigned char* lds, const bf16_t* Ag, const bf16_t* Btg, const int K, const int nM, const int nN, const Epi& E) {
;     ...
;         if (!has_next) break;
; #pragma unroll
;         for (int a = 0; a < 2; ++a)
; #pragma unroll
;             for (int b = 0; b < 2; ++b)
; #pragma unroll
;                 for (int m = 0; m < 4; ++m)
; #pragma unroll
;                     for (int n = 0; n < 2; ++n) acc[a][b][m][n] = (f32x4){0.f, 0.f, 0.f, 0.f};
;         if (pmn != pm) par ^= 1;
;         u = un; pm = pmn; pn = pnn; cA = nA; cB = nB;
	v_pk_fma_f32 v[30:31], v[150:151], v[42:43], v[30:31] op_sel_hi:[1,0,1]
	v_pk_fma_f32 v[28:29], v[148:149], v[42:43], v[28:29] op_sel_hi:[1,0,1] neg_lo:[1,0,0] neg_hi:[1,0,0]
	v_pk_fma_f32 v[30:31], v[42:43], v[30:31], v[158:159] op_sel:[1,0,0]
	v_pk_fma_f32 v[28:29], v[42:43], v[28:29], v[156:157] op_sel:[1,0,0]
	v_pk_fma_f32 v[26:27], v[138:139], v[42:43], v[26:27] op_sel_hi:[1,0,1]
	v_pk_fma_f32 v[24:25], v[136:137], v[42:43], v[24:25] op_sel_hi:[1,0,1] neg_lo:[1,0,0] neg_hi:[1,0,0]
	v_max_f32_e32 v28, 0, v28
	v_max_f32_e32 v29, 0, v29
	v_max_f32_e32 v30, 0, v30
	v_max_f32_e32 v31, 0, v31
	v_pk_fma_f32 v[26:27], v[42:43], v[26:27], v[142:143] op_sel:[1,0,0]
	v_pk_fma_f32 v[24:25], v[42:43], v[24:25], v[140:141] op_sel:[1,0,0]
	v_pk_mul_f32 v[28:29], v[28:29], v[28:29]
	v_pk_mul_f32 v[30:31], v[30:31], v[30:31]
	v_max_f32_e32 v24, 0, v24
	v_max_f32_e32 v25, 0, v25
	v_max_f32_e32 v26, 0, v26
	v_max_f32_e32 v27, 0, v27
	v_cvt_pk_bf16_f32 v28, v28, v29
	v_cvt_pk_bf16_f32 v29, v30, v31
	v_lshl_add_u64 v[30:31], s[86:87], 0, v[40:41]
	v_pk_mul_f32 v[24:25], v[24:25], v[24:25]
	v_pk_mul_f32 v[26:27], v[26:27], v[26:27]
	v_lshl_add_u64 v[30:31], v[30:31], 0, v[164:165]
	v_cvt_pk_bf16_f32 v24, v24, v25
	v_cvt_pk_bf16_f32 v25, v26, v27
	global_store_dwordx2 v[30:31], v[24:25], off offset:32
	v_pk_fma_f32 v[24:25], v[130:131], v[42:43], v[38:39] op_sel_hi:[1,0,1]
	v_pk_fma_f32 v[26:27], v[128:129], v[42:43], v[36:37] op_sel_hi:[1,0,1] neg_lo:[1,0,0] neg_hi:[1,0,0]
	v_pk_fma_f32 v[24:25], v[42:43], v[24:25], v[134:135] op_sel:[1,0,0]
	v_pk_fma_f32 v[26:27], v[42:43], v[26:27], v[132:133] op_sel:[1,0,0]
	v_max_f32_e32 v24, 0, v24
	v_max_f32_e32 v26, 0, v26
	v_max_f32_e32 v27, 0, v27
	v_max_f32_e32 v25, 0, v25
	v_pk_mul_f32 v[26:27], v[26:27], v[26:27]
	v_pk_mul_f32 v[24:25], v[24:25], v[24:25]
	v_cvt_pk_bf16_f32 v26, v26, v27
	v_cvt_pk_bf16_f32 v27, v24, v25
	global_store_dwordx2 v[30:31], v[26:27], off offset:256
	v_pk_fma_f32 v[24:25], v[126:127], v[42:43], v[34:35] op_sel_hi:[1,0,1]
	v_pk_fma_f32 v[26:27], v[124:125], v[42:43], v[32:33] op_sel_hi:[1,0,1] neg_lo:[1,0,0] neg_hi:[1,0,0]
	v_pk_fma_f32 v[24:25], v[42:43], v[24:25], v[154:155] op_sel:[1,0,0]
	v_pk_fma_f32 v[26:27], v[42:43], v[26:27], v[152:153] op_sel:[1,0,0]
	v_max_f32_e32 v24, 0, v24
	v_max_f32_e32 v26, 0, v26
	v_max_f32_e32 v27, 0, v27
	v_max_f32_e32 v25, 0, v25
	v_pk_mul_f32 v[26:27], v[26:27], v[26:27]
	v_pk_mul_f32 v[24:25], v[24:25], v[24:25]
	v_cvt_pk_bf16_f32 v26, v26, v27
	v_cvt_pk_bf16_f32 v27, v24, v25
	global_store_dwordx2 v[30:31], v[28:29], off
	global_store_dwordx2 v[30:31], v[26:27], off offset:288
	ds_read_b64 v[26:27], v187 offset:1408
	v_add_u32_e32 v24, s15, v184
	v_ashrrev_i32_e32 v25, 31, v24
	v_lshlrev_b64 v[24:25], 13, v[24:25]
	s_mov_b64 s[14:15], -1
	s_waitcnt lgkmcnt(0)
	v_pk_fma_f32 v[14:15], v[150:151], v[26:27], v[14:15] op_sel_hi:[1,0,1]
	v_pk_fma_f32 v[12:13], v[148:149], v[26:27], v[12:13] op_sel_hi:[1,0,1] neg_lo:[1,0,0] neg_hi:[1,0,0]
	v_pk_fma_f32 v[14:15], v[26:27], v[14:15], v[158:159] op_sel:[1,0,0]
	v_pk_fma_f32 v[12:13], v[26:27], v[12:13], v[156:157] op_sel:[1,0,0]
	v_pk_fma_f32 v[10:11], v[138:139], v[26:27], v[10:11] op_sel_hi:[1,0,1]
	v_pk_fma_f32 v[8:9], v[136:137], v[26:27], v[8:9] op_sel_hi:[1,0,1] neg_lo:[1,0,0] neg_hi:[1,0,0]
	v_max_f32_e32 v12, 0, v12
	v_max_f32_e32 v13, 0, v13
	v_max_f32_e32 v14, 0, v14
	v_max_f32_e32 v15, 0, v15
	v_pk_fma_f32 v[10:11], v[26:27], v[10:11], v[142:143] op_sel:[1,0,0]
	v_pk_fma_f32 v[8:9], v[26:27], v[8:9], v[140:141] op_sel:[1,0,0]
	v_pk_mul_f32 v[12:13], v[12:13], v[12:13]
	v_pk_mul_f32 v[14:15], v[14:15], v[14:15]
	v_max_f32_e32 v8, 0, v8
	v_max_f32_e32 v9, 0, v9
	v_max_f32_e32 v10, 0, v10
	v_max_f32_e32 v11, 0, v11
	v_cvt_pk_bf16_f32 v12, v12, v13
	v_cvt_pk_bf16_f32 v13, v14, v15
	v_lshl_add_u64 v[14:15], s[86:87], 0, v[24:25]
	v_pk_mul_f32 v[8:9], v[8:9], v[8:9]
	v_pk_mul_f32 v[10:11], v[10:11], v[10:11]
	v_lshl_add_u64 v[14:15], v[14:15], 0, v[164:165]
	v_cvt_pk_bf16_f32 v8, v8, v9
	v_cvt_pk_bf16_f32 v9, v10, v11
	global_store_dwordx2 v[14:15], v[8:9], off offset:32
	v_pk_fma_f32 v[8:9], v[130:131], v[26:27], v[22:23] op_sel_hi:[1,0,1]
	v_pk_fma_f32 v[10:11], v[128:129], v[26:27], v[20:21] op_sel_hi:[1,0,1] neg_lo:[1,0,0] neg_hi:[1,0,0]
	v_pk_fma_f32 v[8:9], v[26:27], v[8:9], v[134:135] op_sel:[1,0,0]
	v_pk_fma_f32 v[10:11], v[26:27], v[10:11], v[132:133] op_sel:[1,0,0]
	v_max_f32_e32 v8, 0, v8
	v_max_f32_e32 v10, 0, v10
	v_max_f32_e32 v11, 0, v11
	v_max_f32_e32 v9, 0, v9
	v_pk_mul_f32 v[10:11], v[10:11], v[10:11]
	v_pk_mul_f32 v[8:9], v[8:9], v[8:9]
	v_cvt_pk_bf16_f32 v10, v10, v11
	v_cvt_pk_bf16_f32 v11, v8, v9
	global_store_dwordx2 v[14:15], v[10:11], off offset:256
	v_pk_fma_f32 v[8:9], v[126:127], v[26:27], v[18:19] op_sel_hi:[1,0,1]
	v_pk_fma_f32 v[10:11], v[124:125], v[26:27], v[16:17] op_sel_hi:[1,0,1] neg_lo:[1,0,0] neg_hi:[1,0,0]
	v_pk_fma_f32 v[8:9], v[26:27], v[8:9], v[154:155] op_sel:[1,0,0]
	v_pk_fma_f32 v[10:11], v[26:27], v[10:11], v[152:153] op_sel:[1,0,0]
	v_max_f32_e32 v8, 0, v8
	v_max_f32_e32 v10, 0, v10
	v_max_f32_e32 v11, 0, v11
	v_max_f32_e32 v9, 0, v9
	v_pk_mul_f32 v[10:11], v[10:11], v[10:11]
	v_pk_mul_f32 v[8:9], v[8:9], v[8:9]
	v_cvt_pk_bf16_f32 v10, v10, v11
	v_cvt_pk_bf16_f32 v11, v8, v9
	global_store_dwordx2 v[14:15], v[12:13], off
	global_store_dwordx2 v[14:15], v[10:11], off offset:288
	s_cbranch_vccz .LBB0_71
	s_cmp_lg_u32 s67, s66
	s_cselect_b64 s[14:15], -1, 0
	v_cndmask_b32_e64 v8, 0, 1, s[14:15]
	s_mov_b64 s[14:15], 0
	v_readfirstlane_b32 s12, v8
	s_xor_b32 s64, s64, s12
	s_branch .LBB0_71
